# robustness only: final-norm slot poll spin cap raised from 2048 to 32767 iterations, otherwise identical to the previous best
# speedup vs baseline: 1.0042x; 1.0042x over previous
;     __device__ __forceinline__ void fused(f32x4 (&acc)[2][2][4][2], const Unit& u, int wr, int wc, int fr, int fq, PG8_LAS unsigned char* lds, int wid, int lane) const {
;     ...
;         if (lane < 32) {
;             const float* slot = xbuf + (size_t)(u.pm * 256 + row) * 8; float t = 0.f;
; #pragma unroll
;             for (int k = 0; k < 8; ++k) t += __hip_atomic_load(slot + k, __ATOMIC_RELAXED, __HIP_MEMORY_SCOPE_AGENT);
;             S[row] = rsqrtf(t * (1.0f / D) + EPS);
;         }
;         asm volatile("s_waitcnt vmcnt(0) lgkmcnt(0)" ::: "memory"); __builtin_amdgcn_s_barrier(); asm volatile("" ::: "memory");
;         f32x4 g[2][2];
; #pragma unroll
;         for (int bj = 0; bj < 2; ++bj) { g[bj][0] = *(const f32x4*)(gain + col0 + bj * 128); g[bj][1] = *(const f32x4*)(gain + col0 + bj * 128 + 4); }
.LBB0_1929:
	s_or_b64 exec, exec, s[4:5]
	v_readlane_b32 s98, v254, 0
	v_readlane_b32 s99, v254, 1
	s_nop 3
	v_lshl_add_u64 v[252:253], v[132:133], 2, s[98:99]
	global_load_dwordx4 v[236:239], v[252:253], off
	global_load_dwordx4 v[240:243], v[252:253], off offset:16
	global_load_dwordx4 v[244:247], v[252:253], off offset:512
	global_load_dwordx4 v[248:251], v[252:253], off offset:528
	s_and_saveexec_b64 s[4:5], s[0:1]
	v_lshlrev_b64 v[2:3], 5, v[2:3]
	v_lshl_add_u64 v[2:3], s[2:3], 0, v[2:3]
	s_movk_i32 s12, 0x7fff
